# LRU rescan loop: next batch's 32 loads prefetched into a spare register set (waits counted past the stores), on top of v41
# speedup vs baseline: 1.0124x; 1.0027x over previous
; __global__ void __launch_bounds__(512, 2) mega(Params p, int ph_lo, int ph_hi) {
;     ...
;             const unsigned* src = LAU + (size_t)cidx * 128 * 1024 + ch;
;             const size_t trow = (size_t)cidx * 128;
; #pragma unroll 1
;             for (int t0 = 0; t0 < 128; t0 += 16) {
;                 unsigned w[16]; bf16_t yv[16];
; #pragma unroll
;                 for (int u = 0; u < 16; ++u) { w[u] = src[(size_t)(t0 + u) * 1024]; yv[u] = BIG[(trow + t0 + u) * INC + 1024 + ch]; }
.LBB0_557:
	s_or_b64 exec, exec, s[10:11]
	v_and_b32_e32 v8, 0x3ff, v12
	v_ashrrev_i32_e32 v7, 31, v6
	v_lshlrev_b32_e32 v9, 1, v8
	v_lshlrev_b64 v[2:3], 19, v[6:7]
	v_mul_hi_i32_i24_e32 v7, 0x180000, v6
	v_mul_i32_i24_e32 v6, 0x180000, v6
	v_or_b32_e32 v4, v2, v9
	v_mov_b32_e32 v5, v3
	v_or_b32_e32 v6, v6, v9
	v_lshl_or_b32 v2, v8, 2, v2
	s_mov_b32 s10, -16
	v_lshl_add_u64 v[184:185], s[90:91], 0, v[2:3]
	v_lshl_add_u64 v[186:187], s[90:91], 0, v[6:7]
	s_mov_b64 s[100:101], 0x16800000
	v_lshl_add_u64 v[184:185], v[184:185], 0, s[100:101]
	s_mov_b64 s[100:101], 0xa800800
	v_lshl_add_u64 v[186:187], v[186:187], 0, s[100:101]
	s_mov_b64 s[100:101], 0x1000
	global_load_dword v120, v[184:185], off
	v_lshl_add_u64 v[184:185], v[184:185], 0, s[100:101]
	global_load_dword v121, v[184:185], off
	v_lshl_add_u64 v[184:185], v[184:185], 0, s[100:101]
	global_load_dword v122, v[184:185], off
	v_lshl_add_u64 v[184:185], v[184:185], 0, s[100:101]
	global_load_dword v123, v[184:185], off
	v_lshl_add_u64 v[184:185], v[184:185], 0, s[100:101]
	global_load_dword v124, v[184:185], off
	v_lshl_add_u64 v[184:185], v[184:185], 0, s[100:101]
	global_load_dword v125, v[184:185], off
	v_lshl_add_u64 v[184:185], v[184:185], 0, s[100:101]
	global_load_dword v126, v[184:185], off
	v_lshl_add_u64 v[184:185], v[184:185], 0, s[100:101]
	global_load_dword v127, v[184:185], off
	v_lshl_add_u64 v[184:185], v[184:185], 0, s[100:101]
	global_load_dword v128, v[184:185], off
	v_lshl_add_u64 v[184:185], v[184:185], 0, s[100:101]
	global_load_dword v129, v[184:185], off
	v_lshl_add_u64 v[184:185], v[184:185], 0, s[100:101]
	global_load_dword v130, v[184:185], off
	v_lshl_add_u64 v[184:185], v[184:185], 0, s[100:101]
	global_load_dword v131, v[184:185], off
	v_lshl_add_u64 v[184:185], v[184:185], 0, s[100:101]
	global_load_dword v132, v[184:185], off
	v_lshl_add_u64 v[184:185], v[184:185], 0, s[100:101]
	global_load_dword v133, v[184:185], off
	v_lshl_add_u64 v[184:185], v[184:185], 0, s[100:101]
	global_load_dword v134, v[184:185], off
	v_lshl_add_u64 v[184:185], v[184:185], 0, s[100:101]
	global_load_dword v135, v[184:185], off
	v_lshl_add_u64 v[184:185], v[184:185], 0, s[100:101]
	s_mov_b64 s[100:101], 0x3000
	global_load_ushort v136, v[186:187], off
	v_lshl_add_u64 v[186:187], v[186:187], 0, s[100:101]
	global_load_ushort v137, v[186:187], off
	v_lshl_add_u64 v[186:187], v[186:187], 0, s[100:101]
	global_load_ushort v138, v[186:187], off
	v_lshl_add_u64 v[186:187], v[186:187], 0, s[100:101]
	global_load_ushort v139, v[186:187], off
	v_lshl_add_u64 v[186:187], v[186:187], 0, s[100:101]
	global_load_ushort v140, v[186:187], off
	v_lshl_add_u64 v[186:187], v[186:187], 0, s[100:101]
	global_load_ushort v141, v[186:187], off
	v_lshl_add_u64 v[186:187], v[186:187], 0, s[100:101]
	global_load_ushort v142, v[186:187], off
	v_lshl_add_u64 v[186:187], v[186:187], 0, s[100:101]
	global_load_ushort v143, v[186:187], off
	v_lshl_add_u64 v[186:187], v[186:187], 0, s[100:101]
	global_load_ushort v144, v[186:187], off
	v_lshl_add_u64 v[186:187], v[186:187], 0, s[100:101]
	global_load_ushort v145, v[186:187], off
	v_lshl_add_u64 v[186:187], v[186:187], 0, s[100:101]
	global_load_ushort v146, v[186:187], off
	v_lshl_add_u64 v[186:187], v[186:187], 0, s[100:101]
	global_load_ushort v147, v[186:187], off
	v_lshl_add_u64 v[186:187], v[186:187], 0, s[100:101]
	global_load_ushort v148, v[186:187], off
	v_lshl_add_u64 v[186:187], v[186:187], 0, s[100:101]
	global_load_ushort v149, v[186:187], off
	v_lshl_add_u64 v[186:187], v[186:187], 0, s[100:101]
	global_load_ushort v150, v[186:187], off
	v_lshl_add_u64 v[186:187], v[186:187], 0, s[100:101]
	global_load_ushort v151, v[186:187], off
	v_lshl_add_u64 v[186:187], v[186:187], 0, s[100:101]
	s_waitcnt vmcnt(0)
	s_branch .Llru_enter
.LBB0_558:
	s_waitcnt vmcnt(16)
.Llru_enter:
	v_mov_b32_e32 v152, v120
	v_mov_b32_e32 v153, v121
	v_mov_b32_e32 v154, v122
	v_mov_b32_e32 v155, v123
	v_mov_b32_e32 v156, v124
	v_mov_b32_e32 v157, v125
	v_mov_b32_e32 v158, v126
	v_mov_b32_e32 v159, v127
	v_mov_b32_e32 v160, v128
	v_mov_b32_e32 v161, v129
	v_mov_b32_e32 v162, v130
	v_mov_b32_e32 v163, v131
	v_mov_b32_e32 v164, v132
	v_mov_b32_e32 v165, v133
	v_mov_b32_e32 v166, v134
	v_mov_b32_e32 v167, v135
	v_mov_b32_e32 v168, v136
	v_mov_b32_e32 v169, v137
	v_mov_b32_e32 v170, v138
	v_mov_b32_e32 v171, v139
	v_mov_b32_e32 v172, v140
	v_mov_b32_e32 v173, v141
	v_mov_b32_e32 v174, v142
	v_mov_b32_e32 v175, v143
	v_mov_b32_e32 v176, v144
	v_mov_b32_e32 v177, v145
	v_mov_b32_e32 v178, v146
	v_mov_b32_e32 v179, v147
	v_mov_b32_e32 v180, v148
	v_mov_b32_e32 v181, v149
	v_mov_b32_e32 v182, v150
	v_mov_b32_e32 v183, v151
	s_cmpk_ge_i32 s10, 0x60
	s_cbranch_scc1 .Llru_nopf
; __device__ __forceinline__ float bflo(unsigned w) { return __uint_as_float(w << 16); }
; __device__ __forceinline__ float bfhi(unsigned w) { return __uint_as_float(w & 0xffff0000u); }
; __global__ void __launch_bounds__(512, 2) mega(Params p, int ph_lo, int ph_hi) {
;     ...
;             for (int t0 = 0; t0 < 128; t0 += 16) {
;                 unsigned w[16]; bf16_t yv[16];
; #pragma unroll
;                 for (int u = 0; u < 16; ++u) { w[u] = src[(size_t)(t0 + u) * 1024]; yv[u] = BIG[(trow + t0 + u) * INC + 1024 + ch]; }
; #pragma unroll
;                 for (int u = 0; u < 16; ++u) {
;                     hst = __expf(bflo(w[u])) * hst + bfhi(w[u]);
	s_mov_b64 s[100:101], 0x1000
	global_load_dword v120, v[184:185], off
	v_lshl_add_u64 v[184:185], v[184:185], 0, s[100:101]
	global_load_dword v121, v[184:185], off
	v_lshl_add_u64 v[184:185], v[184:185], 0, s[100:101]
	global_load_dword v122, v[184:185], off
	v_lshl_add_u64 v[184:185], v[184:185], 0, s[100:101]
	global_load_dword v123, v[184:185], off
	v_lshl_add_u64 v[184:185], v[184:185], 0, s[100:101]
	global_load_dword v124, v[184:185], off
	v_lshl_add_u64 v[184:185], v[184:185], 0, s[100:101]
	global_load_dword v125, v[184:185], off
	v_lshl_add_u64 v[184:185], v[184:185], 0, s[100:101]
	global_load_dword v126, v[184:185], off
	v_lshl_add_u64 v[184:185], v[184:185], 0, s[100:101]
	global_load_dword v127, v[184:185], off
	v_lshl_add_u64 v[184:185], v[184:185], 0, s[100:101]
	global_load_dword v128, v[184:185], off
	v_lshl_add_u64 v[184:185], v[184:185], 0, s[100:101]
	global_load_dword v129, v[184:185], off
	v_lshl_add_u64 v[184:185], v[184:185], 0, s[100:101]
	global_load_dword v130, v[184:185], off
	v_lshl_add_u64 v[184:185], v[184:185], 0, s[100:101]
	global_load_dword v131, v[184:185], off
	v_lshl_add_u64 v[184:185], v[184:185], 0, s[100:101]
	global_load_dword v132, v[184:185], off
	v_lshl_add_u64 v[184:185], v[184:185], 0, s[100:101]
	global_load_dword v133, v[184:185], off
	v_lshl_add_u64 v[184:185], v[184:185], 0, s[100:101]
	global_load_dword v134, v[184:185], off
	v_lshl_add_u64 v[184:185], v[184:185], 0, s[100:101]
	global_load_dword v135, v[184:185], off
	v_lshl_add_u64 v[184:185], v[184:185], 0, s[100:101]
	s_mov_b64 s[100:101], 0x3000
	global_load_ushort v136, v[186:187], off
	v_lshl_add_u64 v[186:187], v[186:187], 0, s[100:101]
	global_load_ushort v137, v[186:187], off
	v_lshl_add_u64 v[186:187], v[186:187], 0, s[100:101]
	global_load_ushort v138, v[186:187], off
	v_lshl_add_u64 v[186:187], v[186:187], 0, s[100:101]
	global_load_ushort v139, v[186:187], off
	v_lshl_add_u64 v[186:187], v[186:187], 0, s[100:101]
	global_load_ushort v140, v[186:187], off
	v_lshl_add_u64 v[186:187], v[186:187], 0, s[100:101]
	global_load_ushort v141, v[186:187], off
	v_lshl_add_u64 v[186:187], v[186:187], 0, s[100:101]
	global_load_ushort v142, v[186:187], off
	v_lshl_add_u64 v[186:187], v[186:187], 0, s[100:101]
	global_load_ushort v143, v[186:187], off
	v_lshl_add_u64 v[186:187], v[186:187], 0, s[100:101]
	global_load_ushort v144, v[186:187], off
	v_lshl_add_u64 v[186:187], v[186:187], 0, s[100:101]
	global_load_ushort v145, v[186:187], off
	v_lshl_add_u64 v[186:187], v[186:187], 0, s[100:101]
	global_load_ushort v146, v[186:187], off
	v_lshl_add_u64 v[186:187], v[186:187], 0, s[100:101]
	global_load_ushort v147, v[186:187], off
	v_lshl_add_u64 v[186:187], v[186:187], 0, s[100:101]
	global_load_ushort v148, v[186:187], off
	v_lshl_add_u64 v[186:187], v[186:187], 0, s[100:101]
	global_load_ushort v149, v[186:187], off
	v_lshl_add_u64 v[186:187], v[186:187], 0, s[100:101]
	global_load_ushort v150, v[186:187], off
	v_lshl_add_u64 v[186:187], v[186:187], 0, s[100:101]
	global_load_ushort v151, v[186:187], off
	v_lshl_add_u64 v[186:187], v[186:187], 0, s[100:101]
.Llru_nopf:
	v_lshl_add_u64 v[8:9], s[90:91], 0, v[2:3]
	v_add_co_u32_e32 v10, vcc, 0x16800000, v8
	s_add_i32 s10, s10, 16
	s_nop 0
	v_addc_co_u32_e32 v11, vcc, 0, v9, vcc
	v_mov_b32_e32 v30, v152
	v_add_co_u32_e32 v16, vcc, 0x16801000, v8
	v_lshl_add_u64 v[2:3], v[2:3], 0, s[6:7]
	s_nop 0
	v_addc_co_u32_e32 v17, vcc, 0, v9, vcc
	v_mov_b32_e32 v31, v153
	v_add_co_u32_e32 v16, vcc, 0x16802000, v8
	s_cmpk_gt_u32 s10, 0x6f
	s_nop 0
	v_addc_co_u32_e32 v17, vcc, 0, v9, vcc
	v_mov_b32_e32 v32, v154
	v_add_co_u32_e32 v16, vcc, 0x16803000, v8
	s_nop 1
	v_addc_co_u32_e32 v17, vcc, 0, v9, vcc
	v_mov_b32_e32 v27, v155
	v_add_co_u32_e32 v16, vcc, 0x16804000, v8
	s_nop 1
	v_addc_co_u32_e32 v17, vcc, 0, v9, vcc
	v_mov_b32_e32 v26, v156
	v_add_co_u32_e32 v16, vcc, 0x16805000, v8
	s_nop 1
	v_addc_co_u32_e32 v17, vcc, 0, v9, vcc
	v_mov_b32_e32 v25, v157
	v_add_co_u32_e32 v16, vcc, 0x16806000, v8
	s_nop 1
	v_addc_co_u32_e32 v17, vcc, 0, v9, vcc
	v_mov_b32_e32 v24, v158
	v_add_co_u32_e32 v16, vcc, 0x16807000, v8
	s_nop 1
	v_addc_co_u32_e32 v17, vcc, 0, v9, vcc
	v_mov_b32_e32 v23, v159
	v_add_co_u32_e32 v16, vcc, 0x16808000, v8
	s_nop 1
	v_addc_co_u32_e32 v17, vcc, 0, v9, vcc
	v_mov_b32_e32 v22, v160
	v_add_co_u32_e32 v16, vcc, 0x16809000, v8
	s_nop 1
	v_addc_co_u32_e32 v17, vcc, 0, v9, vcc
	v_mov_b32_e32 v21, v161
	v_add_co_u32_e32 v16, vcc, 0x1680a000, v8
	s_nop 1
	v_addc_co_u32_e32 v17, vcc, 0, v9, vcc
	v_mov_b32_e32 v20, v162
	v_add_co_u32_e32 v16, vcc, 0x1680b000, v8
	s_nop 1
	v_addc_co_u32_e32 v17, vcc, 0, v9, vcc
	v_mov_b32_e32 v19, v163
	v_add_co_u32_e32 v16, vcc, 0x1680c000, v8
	s_nop 1
	v_addc_co_u32_e32 v17, vcc, 0, v9, vcc
	v_mov_b32_e32 v18, v164
	v_add_co_u32_e32 v16, vcc, 0x1680d000, v8
	s_nop 1
	v_addc_co_u32_e32 v17, vcc, 0, v9, vcc
	v_add_co_u32_e32 v28, vcc, 0x1680e000, v8
	v_mov_b32_e32 v17, v165
	s_nop 0
	v_addc_co_u32_e32 v29, vcc, 0, v9, vcc
	v_add_co_u32_e32 v8, vcc, 0x1680f000, v8
	s_nop 1
	v_addc_co_u32_e32 v9, vcc, 0, v9, vcc
	v_mov_b32_e32 v15, v167
	v_lshlrev_b32_e32 v8, 16, v30
	v_mul_f32_e32 v8, 0x3fb8aa3b, v8
	v_exp_f32_e32 v8, v8
	v_lshl_add_u64 v[10:11], s[90:91], 0, v[6:7]
	v_and_b32_e32 v30, 0xffff0000, v30
	v_lshl_add_u64 v[6:7], v[6:7], 0, s[8:9]
	v_fmac_f32_e32 v30, v14, v8
	v_add_co_u32_e32 v8, vcc, 0xa800000, v10
	s_nop 1
	v_addc_co_u32_e32 v9, vcc, 0, v11, vcc
	v_mov_b32_e32 v8, v168
	v_lshlrev_b32_e32 v8, 16, v8
	v_mul_f32_e32 v9, 0x3d372713, v8
	v_mul_f32_e32 v9, v9, v8
	v_fma_f32 v9, v9, v8, v8
	v_mul_f32_e32 v9, 0x3f4c422a, v9
	v_add_f32_e32 v9, v9, v9
; __device__ __forceinline__ float bf2f(bf16_t b) { return __uint_as_float(((unsigned)b) << 16); }
; __device__ __forceinline__ float bflo(unsigned w) { return __uint_as_float(w << 16); }
; __device__ __forceinline__ float bfhi(unsigned w) { return __uint_as_float(w & 0xffff0000u); }
; __device__ __forceinline__ float gelu_tanh(float y) { const float z = 0.7978845608028654f * (y + 0.044715f * y * y * y); const float t = 1.0f - 2.0f / (__expf(2.0f * z) + 1.0f); return 0.5f * y * (1.0f + t); }
; __global__ void __launch_bounds__(512, 2) mega(Params p, int ph_lo, int ph_hi) {
;     ...
;                 for (int u = 0; u < 16; ++u) { w[u] = src[(size_t)(t0 + u) * 1024]; yv[u] = BIG[(trow + t0 + u) * INC + 1024 + ch]; }
; #pragma unroll
;                 for (int u = 0; u < 16; ++u) {
;                     hst = __expf(bflo(w[u])) * hst + bfhi(w[u]);
;                     XN[(trow + t0 + u) * DM + ch] = (bf16_t)(pk2(hst * gelu_tanh(bf2f(yv[u])), 0.f) & 0xffffu);
	v_mul_f32_e32 v9, 0x3fb8aa3b, v9
	v_exp_f32_e32 v9, v9
	v_mov_b32_e32 v16, v166
	v_mul_f32_e32 v8, 0.5, v8
	v_add_f32_e32 v9, 1.0, v9
	v_div_scale_f32 v14, s[12:13], v9, v9, 2.0
	v_rcp_f32_e32 v28, v14
	s_nop 0
	v_fma_f32 v29, -v14, v28, 1.0
	v_fmac_f32_e32 v28, v29, v28
	v_div_scale_f32 v29, vcc, 2.0, v9, 2.0
	v_mul_f32_e32 v33, v29, v28
	v_fma_f32 v34, -v14, v33, v29
	v_fmac_f32_e32 v33, v34, v28
	v_fma_f32 v14, -v14, v33, v29
	v_div_fmas_f32 v14, v14, v28, v33
	v_add_co_u32_e32 v28, vcc, s3, v10
	v_div_fixup_f32 v9, v14, v9, 2.0
	s_nop 0
	v_addc_co_u32_e32 v29, vcc, 0, v11, vcc
	v_mov_b32_e32 v33, v169
	v_add_co_u32_e32 v28, vcc, s14, v10
	v_sub_f32_e32 v9, 1.0, v9
	s_nop 0
	v_addc_co_u32_e32 v29, vcc, 0, v11, vcc
	v_mov_b32_e32 v34, v170
	v_add_co_u32_e32 v28, vcc, s15, v10
	v_add_f32_e32 v9, 1.0, v9
	s_nop 0
	v_addc_co_u32_e32 v29, vcc, 0, v11, vcc
	v_mov_b32_e32 v35, v171
	v_add_co_u32_e32 v28, vcc, s16, v10
	v_mul_f32_e32 v8, v8, v9
	s_nop 0
	v_addc_co_u32_e32 v29, vcc, 0, v11, vcc
	v_mov_b32_e32 v36, v172
	v_add_co_u32_e32 v28, vcc, s17, v10
	v_mul_f32_e32 v8, v30, v8
	s_nop 0
	v_addc_co_u32_e32 v29, vcc, 0, v11, vcc
	v_mov_b32_e32 v37, v173
	v_add_co_u32_e32 v28, vcc, s18, v10
	v_cvt_pk_bf16_f32 v14, v8, s0
	s_nop 0
	v_addc_co_u32_e32 v29, vcc, 0, v11, vcc
	v_mov_b32_e32 v38, v174
	v_add_co_u32_e32 v28, vcc, s19, v10
	v_lshl_add_u64 v[8:9], s[90:91], 0, v[4:5]
	s_nop 0
	v_addc_co_u32_e32 v29, vcc, 0, v11, vcc
	v_mov_b32_e32 v39, v175
	v_add_co_u32_e32 v28, vcc, s20, v10
	v_lshl_add_u64 v[4:5], v[4:5], 0, s[6:7]
	s_nop 0
	v_addc_co_u32_e32 v29, vcc, 0, v11, vcc
	v_mov_b32_e32 v40, v176
	v_add_co_u32_e32 v28, vcc, s21, v10
	s_nop 1
	v_addc_co_u32_e32 v29, vcc, 0, v11, vcc
	v_mov_b32_e32 v41, v177
	v_add_co_u32_e32 v28, vcc, s22, v10
	s_nop 1
	v_addc_co_u32_e32 v29, vcc, 0, v11, vcc
	v_mov_b32_e32 v42, v178
	v_add_co_u32_e32 v28, vcc, s23, v10
	s_nop 1
	v_addc_co_u32_e32 v29, vcc, 0, v11, vcc
	v_mov_b32_e32 v43, v179
	v_add_co_u32_e32 v28, vcc, s24, v10
	s_nop 1
	v_addc_co_u32_e32 v29, vcc, 0, v11, vcc
	v_mov_b32_e32 v44, v180
	v_add_co_u32_e32 v28, vcc, s25, v10
	s_nop 1
	v_addc_co_u32_e32 v29, vcc, 0, v11, vcc
	v_mov_b32_e32 v45, v181
	v_add_co_u32_e32 v28, vcc, s26, v10
	s_nop 1
	v_addc_co_u32_e32 v29, vcc, 0, v11, vcc
	v_add_co_u32_e32 v10, vcc, s27, v10
	v_mov_b32_e32 v28, v182
	s_nop 0
	v_addc_co_u32_e32 v11, vcc, 0, v11, vcc
	v_mov_b32_e32 v29, v183
	v_add_co_u32_e32 v10, vcc, s28, v8
	s_nop 1
	v_addc_co_u32_e32 v11, vcc, 0, v9, vcc
	global_store_short v[10:11], v14, off offset:-4096
	v_lshlrev_b32_e32 v14, 16, v31
	v_mul_f32_e32 v14, 0x3fb8aa3b, v14
	v_exp_f32_e32 v14, v14
	v_and_b32_e32 v31, 0xffff0000, v31
	v_fmac_f32_e32 v31, v30, v14
	v_lshlrev_b32_e32 v14, 16, v33
	v_mul_f32_e32 v30, 0x3d372713, v14
	v_mul_f32_e32 v30, v30, v14
	v_fma_f32 v30, v30, v14, v14
	v_mul_f32_e32 v30, 0x3f4c422a, v30
	v_add_f32_e32 v30, v30, v30
	v_mul_f32_e32 v30, 0x3fb8aa3b, v30
	v_exp_f32_e32 v30, v30
	v_mul_f32_e32 v14, 0.5, v14
	v_add_f32_e32 v30, 1.0, v30
	v_div_scale_f32 v33, s[12:13], v30, v30, 2.0
	v_rcp_f32_e32 v46, v33
	s_nop 0
	v_fma_f32 v47, -v33, v46, 1.0
	v_fmac_f32_e32 v46, v47, v46
	v_div_scale_f32 v47, vcc, 2.0, v30, 2.0
	v_mul_f32_e32 v48, v47, v46
	v_fma_f32 v49, -v33, v48, v47
	v_fmac_f32_e32 v48, v49, v46
	v_fma_f32 v33, -v33, v48, v47
	v_div_fmas_f32 v33, v33, v46, v48
	v_div_fixup_f32 v30, v33, v30, 2.0
	v_sub_f32_e32 v30, 1.0, v30
	v_add_f32_e32 v30, 1.0, v30
	v_mul_f32_e32 v14, v14, v30
	v_mul_f32_e32 v14, v31, v14
	v_cvt_pk_bf16_f32 v14, v14, s0
	global_store_short v[10:11], v14, off
	v_lshlrev_b32_e32 v10, 16, v32
	v_mul_f32_e32 v10, 0x3fb8aa3b, v10
	v_exp_f32_e32 v10, v10
	v_and_b32_e32 v14, 0xffff0000, v32
	v_fmac_f32_e32 v14, v31, v10
	v_lshlrev_b32_e32 v10, 16, v34
	v_mul_f32_e32 v11, 0x3d372713, v10
	v_mul_f32_e32 v11, v11, v10
	v_fma_f32 v11, v11, v10, v10
	v_mul_f32_e32 v11, 0x3f4c422a, v11
	v_add_f32_e32 v11, v11, v11
	v_mul_f32_e32 v11, 0x3fb8aa3b, v11
	v_exp_f32_e32 v11, v11
	v_mul_f32_e32 v10, 0.5, v10
	v_add_f32_e32 v11, 1.0, v11
	v_div_scale_f32 v30, s[12:13], v11, v11, 2.0
	v_rcp_f32_e32 v31, v30
	s_nop 0
	v_fma_f32 v32, -v30, v31, 1.0
	v_fmac_f32_e32 v31, v32, v31
	v_div_scale_f32 v32, vcc, 2.0, v11, 2.0
	v_mul_f32_e32 v33, v32, v31
	v_fma_f32 v34, -v30, v33, v32
	v_fmac_f32_e32 v33, v34, v31
	v_fma_f32 v30, -v30, v33, v32
	v_div_fmas_f32 v30, v30, v31, v33
	v_div_fixup_f32 v11, v30, v11, 2.0
	v_sub_f32_e32 v11, 1.0, v11
	v_add_f32_e32 v11, 1.0, v11
	v_mul_f32_e32 v10, v10, v11
	v_mul_f32_e32 v10, v14, v10
	v_cvt_pk_bf16_f32 v30, v10, s0
	v_add_co_u32_e32 v10, vcc, s29, v8
	s_nop 1
	v_addc_co_u32_e32 v11, vcc, 0, v9, vcc
	global_store_short v[10:11], v30, off offset:-4096
	v_lshlrev_b32_e32 v30, 16, v27
	v_mul_f32_e32 v30, 0x3fb8aa3b, v30
	v_exp_f32_e32 v30, v30
	v_and_b32_e32 v27, 0xffff0000, v27
	v_fmac_f32_e32 v27, v14, v30
	v_lshlrev_b32_e32 v14, 16, v35
	v_mul_f32_e32 v30, 0x3d372713, v14
	v_mul_f32_e32 v30, v30, v14
	v_fma_f32 v30, v30, v14, v14
	v_mul_f32_e32 v30, 0x3f4c422a, v30
	v_add_f32_e32 v30, v30, v30
	v_mul_f32_e32 v30, 0x3fb8aa3b, v30
	v_exp_f32_e32 v30, v30
	v_mul_f32_e32 v14, 0.5, v14
	v_add_f32_e32 v30, 1.0, v30
	v_div_scale_f32 v31, s[12:13], v30, v30, 2.0
	v_rcp_f32_e32 v32, v31
	s_nop 0
	v_fma_f32 v33, -v31, v32, 1.0
	v_fmac_f32_e32 v32, v33, v32
	v_div_scale_f32 v33, vcc, 2.0, v30, 2.0
	v_mul_f32_e32 v34, v33, v32
	v_fma_f32 v35, -v31, v34, v33
	v_fmac_f32_e32 v34, v35, v32
	v_fma_f32 v31, -v31, v34, v33
	v_div_fmas_f32 v31, v31, v32, v34
	v_div_fixup_f32 v30, v31, v30, 2.0
	v_sub_f32_e32 v30, 1.0, v30
	v_add_f32_e32 v30, 1.0, v30
	v_mul_f32_e32 v14, v14, v30
	v_mul_f32_e32 v14, v27, v14
; __device__ __forceinline__ float bf2f(bf16_t b) { return __uint_as_float(((unsigned)b) << 16); }
; __device__ __forceinline__ float bflo(unsigned w) { return __uint_as_float(w << 16); }
; __device__ __forceinline__ float bfhi(unsigned w) { return __uint_as_float(w & 0xffff0000u); }
; __device__ __forceinline__ float gelu_tanh(float y) { const float z = 0.7978845608028654f * (y + 0.044715f * y * y * y); const float t = 1.0f - 2.0f / (__expf(2.0f * z) + 1.0f); return 0.5f * y * (1.0f + t); }
; __global__ void __launch_bounds__(512, 2) mega(Params p, int ph_lo, int ph_hi) {
;     ...
;                 for (int u = 0; u < 16; ++u) {
;                     hst = __expf(bflo(w[u])) * hst + bfhi(w[u]);
;                     XN[(trow + t0 + u) * DM + ch] = (bf16_t)(pk2(hst * gelu_tanh(bf2f(yv[u])), 0.f) & 0xffffu);
	v_cvt_pk_bf16_f32 v14, v14, s0
	global_store_short v[10:11], v14, off
	v_lshlrev_b32_e32 v10, 16, v26
	v_mul_f32_e32 v10, 0x3fb8aa3b, v10
	v_exp_f32_e32 v10, v10
	v_and_b32_e32 v14, 0xffff0000, v26
	v_fmac_f32_e32 v14, v27, v10
	v_lshlrev_b32_e32 v10, 16, v36
	v_mul_f32_e32 v11, 0x3d372713, v10
	v_mul_f32_e32 v11, v11, v10
	v_fma_f32 v11, v11, v10, v10
	v_mul_f32_e32 v11, 0x3f4c422a, v11
	v_add_f32_e32 v11, v11, v11
	v_mul_f32_e32 v11, 0x3fb8aa3b, v11
	v_exp_f32_e32 v11, v11
	v_mul_f32_e32 v10, 0.5, v10
	v_add_f32_e32 v11, 1.0, v11
	v_div_scale_f32 v26, s[12:13], v11, v11, 2.0
	v_rcp_f32_e32 v27, v26
	s_nop 0
	v_fma_f32 v30, -v26, v27, 1.0
	v_fmac_f32_e32 v27, v30, v27
	v_div_scale_f32 v30, vcc, 2.0, v11, 2.0
	v_mul_f32_e32 v31, v30, v27
	v_fma_f32 v32, -v26, v31, v30
	v_fmac_f32_e32 v31, v32, v27
	v_fma_f32 v26, -v26, v31, v30
	v_div_fmas_f32 v26, v26, v27, v31
	v_div_fixup_f32 v11, v26, v11, 2.0
	v_sub_f32_e32 v11, 1.0, v11
	v_add_f32_e32 v11, 1.0, v11
	v_mul_f32_e32 v10, v10, v11
	v_mul_f32_e32 v10, v14, v10
	v_cvt_pk_bf16_f32 v26, v10, s0
	v_add_co_u32_e32 v10, vcc, s30, v8
	s_nop 1
	v_addc_co_u32_e32 v11, vcc, 0, v9, vcc
	global_store_short v[10:11], v26, off offset:-4096
	v_lshlrev_b32_e32 v26, 16, v25
	v_mul_f32_e32 v26, 0x3fb8aa3b, v26
	v_exp_f32_e32 v26, v26
	v_and_b32_e32 v25, 0xffff0000, v25
	v_fmac_f32_e32 v25, v14, v26
	v_lshlrev_b32_e32 v14, 16, v37
	v_mul_f32_e32 v26, 0x3d372713, v14
	v_mul_f32_e32 v26, v26, v14
	v_fma_f32 v26, v26, v14, v14
	v_mul_f32_e32 v26, 0x3f4c422a, v26
	v_add_f32_e32 v26, v26, v26
	v_mul_f32_e32 v26, 0x3fb8aa3b, v26
	v_exp_f32_e32 v26, v26
	v_mul_f32_e32 v14, 0.5, v14
	v_add_f32_e32 v26, 1.0, v26
	v_div_scale_f32 v27, s[12:13], v26, v26, 2.0
	v_rcp_f32_e32 v30, v27
	s_nop 0
	v_fma_f32 v31, -v27, v30, 1.0
	v_fmac_f32_e32 v30, v31, v30
	v_div_scale_f32 v31, vcc, 2.0, v26, 2.0
	v_mul_f32_e32 v32, v31, v30
	v_fma_f32 v33, -v27, v32, v31
	v_fmac_f32_e32 v32, v33, v30
	v_fma_f32 v27, -v27, v32, v31
	v_div_fmas_f32 v27, v27, v30, v32
	v_div_fixup_f32 v26, v27, v26, 2.0
	v_sub_f32_e32 v26, 1.0, v26
	v_add_f32_e32 v26, 1.0, v26
	v_mul_f32_e32 v14, v14, v26
	v_mul_f32_e32 v14, v25, v14
	v_cvt_pk_bf16_f32 v14, v14, s0
	global_store_short v[10:11], v14, off
	v_lshlrev_b32_e32 v10, 16, v24
	v_mul_f32_e32 v10, 0x3fb8aa3b, v10
	v_exp_f32_e32 v10, v10
	v_and_b32_e32 v14, 0xffff0000, v24
	v_fmac_f32_e32 v14, v25, v10
	v_lshlrev_b32_e32 v10, 16, v38
	v_mul_f32_e32 v11, 0x3d372713, v10
	v_mul_f32_e32 v11, v11, v10
	v_fma_f32 v11, v11, v10, v10
	v_mul_f32_e32 v11, 0x3f4c422a, v11
	v_add_f32_e32 v11, v11, v11
	v_mul_f32_e32 v11, 0x3fb8aa3b, v11
	v_exp_f32_e32 v11, v11
	v_mul_f32_e32 v10, 0.5, v10
	v_add_f32_e32 v11, 1.0, v11
	v_div_scale_f32 v24, s[12:13], v11, v11, 2.0
	v_rcp_f32_e32 v25, v24
	s_nop 0
	v_fma_f32 v26, -v24, v25, 1.0
	v_fmac_f32_e32 v25, v26, v25
	v_div_scale_f32 v26, vcc, 2.0, v11, 2.0
	v_mul_f32_e32 v27, v26, v25
	v_fma_f32 v30, -v24, v27, v26
	v_fmac_f32_e32 v27, v30, v25
	v_fma_f32 v24, -v24, v27, v26
	v_div_fmas_f32 v24, v24, v25, v27
	v_div_fixup_f32 v11, v24, v11, 2.0
	v_sub_f32_e32 v11, 1.0, v11
	v_add_f32_e32 v11, 1.0, v11
	v_mul_f32_e32 v10, v10, v11
	v_mul_f32_e32 v10, v14, v10
	v_cvt_pk_bf16_f32 v24, v10, s0
	v_add_co_u32_e32 v10, vcc, s31, v8
	s_nop 1
	v_addc_co_u32_e32 v11, vcc, 0, v9, vcc
	global_store_short v[10:11], v24, off offset:-4096
	v_lshlrev_b32_e32 v24, 16, v23
	v_mul_f32_e32 v24, 0x3fb8aa3b, v24
	v_exp_f32_e32 v24, v24
	v_and_b32_e32 v23, 0xffff0000, v23
	v_fmac_f32_e32 v23, v14, v24
	v_lshlrev_b32_e32 v14, 16, v39
	v_mul_f32_e32 v24, 0x3d372713, v14
	v_mul_f32_e32 v24, v24, v14
	v_fma_f32 v24, v24, v14, v14
	v_mul_f32_e32 v24, 0x3f4c422a, v24
	v_add_f32_e32 v24, v24, v24
	v_mul_f32_e32 v24, 0x3fb8aa3b, v24
	v_exp_f32_e32 v24, v24
	v_mul_f32_e32 v14, 0.5, v14
	v_add_f32_e32 v24, 1.0, v24
	v_div_scale_f32 v25, s[12:13], v24, v24, 2.0
	v_rcp_f32_e32 v26, v25
	s_nop 0
	v_fma_f32 v27, -v25, v26, 1.0
	v_fmac_f32_e32 v26, v27, v26
	v_div_scale_f32 v27, vcc, 2.0, v24, 2.0
	v_mul_f32_e32 v30, v27, v26
	v_fma_f32 v31, -v25, v30, v27
	v_fmac_f32_e32 v30, v31, v26
	v_fma_f32 v25, -v25, v30, v27
	v_div_fmas_f32 v25, v25, v26, v30
	v_div_fixup_f32 v24, v25, v24, 2.0
	v_sub_f32_e32 v24, 1.0, v24
	v_add_f32_e32 v24, 1.0, v24
	v_mul_f32_e32 v14, v14, v24
	v_mul_f32_e32 v14, v23, v14
	v_cvt_pk_bf16_f32 v14, v14, s0
	global_store_short v[10:11], v14, off
	v_lshlrev_b32_e32 v10, 16, v22
	v_mul_f32_e32 v10, 0x3fb8aa3b, v10
	v_exp_f32_e32 v10, v10
	v_and_b32_e32 v14, 0xffff0000, v22
	v_fmac_f32_e32 v14, v23, v10
	v_lshlrev_b32_e32 v10, 16, v40
	v_mul_f32_e32 v11, 0x3d372713, v10
	v_mul_f32_e32 v11, v11, v10
	v_fma_f32 v11, v11, v10, v10
	v_mul_f32_e32 v11, 0x3f4c422a, v11
	v_add_f32_e32 v11, v11, v11
	v_mul_f32_e32 v11, 0x3fb8aa3b, v11
	v_exp_f32_e32 v11, v11
	v_mul_f32_e32 v10, 0.5, v10
	v_add_f32_e32 v11, 1.0, v11
	v_div_scale_f32 v22, s[12:13], v11, v11, 2.0
	v_rcp_f32_e32 v23, v22
	s_nop 0
	v_fma_f32 v24, -v22, v23, 1.0
	v_fmac_f32_e32 v23, v24, v23
	v_div_scale_f32 v24, vcc, 2.0, v11, 2.0
	v_mul_f32_e32 v25, v24, v23
	v_fma_f32 v26, -v22, v25, v24
	v_fmac_f32_e32 v25, v26, v23
	v_fma_f32 v22, -v22, v25, v24
	v_div_fmas_f32 v22, v22, v23, v25
	v_div_fixup_f32 v11, v22, v11, 2.0
	v_sub_f32_e32 v11, 1.0, v11
	v_add_f32_e32 v11, 1.0, v11
	v_mul_f32_e32 v10, v10, v11
	v_mul_f32_e32 v10, v14, v10
	v_cvt_pk_bf16_f32 v22, v10, s0
	v_add_co_u32_e32 v10, vcc, s33, v8
	s_nop 1
	v_addc_co_u32_e32 v11, vcc, 0, v9, vcc
	global_store_short v[10:11], v22, off offset:-4096
	v_lshlrev_b32_e32 v22, 16, v21
	v_mul_f32_e32 v22, 0x3fb8aa3b, v22
	v_exp_f32_e32 v22, v22
	v_and_b32_e32 v21, 0xffff0000, v21
; __device__ __forceinline__ float bf2f(bf16_t b) { return __uint_as_float(((unsigned)b) << 16); }
; __device__ __forceinline__ float bflo(unsigned w) { return __uint_as_float(w << 16); }
; __device__ __forceinline__ float bfhi(unsigned w) { return __uint_as_float(w & 0xffff0000u); }
; __device__ __forceinline__ float gelu_tanh(float y) { const float z = 0.7978845608028654f * (y + 0.044715f * y * y * y); const float t = 1.0f - 2.0f / (__expf(2.0f * z) + 1.0f); return 0.5f * y * (1.0f + t); }
; __global__ void __launch_bounds__(512, 2) mega(Params p, int ph_lo, int ph_hi) {
;     ...
;                 for (int u = 0; u < 16; ++u) {
;                     hst = __expf(bflo(w[u])) * hst + bfhi(w[u]);
;                     XN[(trow + t0 + u) * DM + ch] = (bf16_t)(pk2(hst * gelu_tanh(bf2f(yv[u])), 0.f) & 0xffffu);
	v_fmac_f32_e32 v21, v14, v22
	v_lshlrev_b32_e32 v14, 16, v41
	v_mul_f32_e32 v22, 0x3d372713, v14
	v_mul_f32_e32 v22, v22, v14
	v_fma_f32 v22, v22, v14, v14
	v_mul_f32_e32 v22, 0x3f4c422a, v22
	v_add_f32_e32 v22, v22, v22
	v_mul_f32_e32 v22, 0x3fb8aa3b, v22
	v_exp_f32_e32 v22, v22
	v_mul_f32_e32 v14, 0.5, v14
	v_add_f32_e32 v22, 1.0, v22
	v_div_scale_f32 v23, s[12:13], v22, v22, 2.0
	v_rcp_f32_e32 v24, v23
	s_nop 0
	v_fma_f32 v25, -v23, v24, 1.0
	v_fmac_f32_e32 v24, v25, v24
	v_div_scale_f32 v25, vcc, 2.0, v22, 2.0
	v_mul_f32_e32 v26, v25, v24
	v_fma_f32 v27, -v23, v26, v25
	v_fmac_f32_e32 v26, v27, v24
	v_fma_f32 v23, -v23, v26, v25
	v_div_fmas_f32 v23, v23, v24, v26
	v_div_fixup_f32 v22, v23, v22, 2.0
	v_sub_f32_e32 v22, 1.0, v22
	v_add_f32_e32 v22, 1.0, v22
	v_mul_f32_e32 v14, v14, v22
	v_mul_f32_e32 v14, v21, v14
	v_cvt_pk_bf16_f32 v14, v14, s0
	global_store_short v[10:11], v14, off
	v_lshlrev_b32_e32 v10, 16, v20
	v_mul_f32_e32 v10, 0x3fb8aa3b, v10
	v_exp_f32_e32 v10, v10
	v_and_b32_e32 v14, 0xffff0000, v20
	v_fmac_f32_e32 v14, v21, v10
	v_lshlrev_b32_e32 v10, 16, v42
	v_mul_f32_e32 v11, 0x3d372713, v10
	v_mul_f32_e32 v11, v11, v10
	v_fma_f32 v11, v11, v10, v10
	v_mul_f32_e32 v11, 0x3f4c422a, v11
	v_add_f32_e32 v11, v11, v11
	v_mul_f32_e32 v11, 0x3fb8aa3b, v11
	v_exp_f32_e32 v11, v11
	v_mul_f32_e32 v10, 0.5, v10
	v_add_f32_e32 v11, 1.0, v11
	v_div_scale_f32 v20, s[12:13], v11, v11, 2.0
	v_rcp_f32_e32 v21, v20
	s_nop 0
	v_fma_f32 v22, -v20, v21, 1.0
	v_fmac_f32_e32 v21, v22, v21
	v_div_scale_f32 v22, vcc, 2.0, v11, 2.0
	v_mul_f32_e32 v23, v22, v21
	v_fma_f32 v24, -v20, v23, v22
	v_fmac_f32_e32 v23, v24, v21
	v_fma_f32 v20, -v20, v23, v22
	v_div_fmas_f32 v20, v20, v21, v23
	v_div_fixup_f32 v11, v20, v11, 2.0
	v_sub_f32_e32 v11, 1.0, v11
	v_add_f32_e32 v11, 1.0, v11
	v_mul_f32_e32 v10, v10, v11
	v_mul_f32_e32 v10, v14, v10
	v_cvt_pk_bf16_f32 v20, v10, s0
	v_add_co_u32_e32 v10, vcc, s34, v8
	s_nop 1
	v_addc_co_u32_e32 v11, vcc, 0, v9, vcc
	global_store_short v[10:11], v20, off offset:-4096
	v_lshlrev_b32_e32 v20, 16, v19
	v_mul_f32_e32 v20, 0x3fb8aa3b, v20
	v_exp_f32_e32 v20, v20
	v_and_b32_e32 v19, 0xffff0000, v19
	v_fmac_f32_e32 v19, v14, v20
	v_lshlrev_b32_e32 v14, 16, v43
	v_mul_f32_e32 v20, 0x3d372713, v14
	v_mul_f32_e32 v20, v20, v14
	v_fma_f32 v20, v20, v14, v14
	v_mul_f32_e32 v20, 0x3f4c422a, v20
	v_add_f32_e32 v20, v20, v20
	v_mul_f32_e32 v20, 0x3fb8aa3b, v20
	v_exp_f32_e32 v20, v20
	v_mul_f32_e32 v14, 0.5, v14
	v_add_f32_e32 v20, 1.0, v20
	v_div_scale_f32 v21, s[12:13], v20, v20, 2.0
	v_rcp_f32_e32 v22, v21
	s_nop 0
	v_fma_f32 v23, -v21, v22, 1.0
	v_fmac_f32_e32 v22, v23, v22
	v_div_scale_f32 v23, vcc, 2.0, v20, 2.0
	v_mul_f32_e32 v24, v23, v22
	v_fma_f32 v25, -v21, v24, v23
	v_fmac_f32_e32 v24, v25, v22
	v_fma_f32 v21, -v21, v24, v23
	v_div_fmas_f32 v21, v21, v22, v24
	v_div_fixup_f32 v20, v21, v20, 2.0
	v_sub_f32_e32 v20, 1.0, v20
	v_add_f32_e32 v20, 1.0, v20
	v_mul_f32_e32 v14, v14, v20
	v_mul_f32_e32 v14, v19, v14
	v_cvt_pk_bf16_f32 v14, v14, s0
	global_store_short v[10:11], v14, off
	v_lshlrev_b32_e32 v10, 16, v18
	v_mul_f32_e32 v10, 0x3fb8aa3b, v10
	v_exp_f32_e32 v10, v10
	v_and_b32_e32 v14, 0xffff0000, v18
	v_fmac_f32_e32 v14, v19, v10
	v_lshlrev_b32_e32 v10, 16, v44
	v_mul_f32_e32 v11, 0x3d372713, v10
	v_mul_f32_e32 v11, v11, v10
	v_fma_f32 v11, v11, v10, v10
	v_mul_f32_e32 v11, 0x3f4c422a, v11
	v_add_f32_e32 v11, v11, v11
	v_mul_f32_e32 v11, 0x3fb8aa3b, v11
	v_exp_f32_e32 v11, v11
	v_mul_f32_e32 v10, 0.5, v10
	v_add_f32_e32 v11, 1.0, v11
	v_div_scale_f32 v18, s[12:13], v11, v11, 2.0
	v_rcp_f32_e32 v19, v18
	s_nop 0
	v_fma_f32 v20, -v18, v19, 1.0
	v_fmac_f32_e32 v19, v20, v19
	v_div_scale_f32 v20, vcc, 2.0, v11, 2.0
	v_mul_f32_e32 v21, v20, v19
	v_fma_f32 v22, -v18, v21, v20
	v_fmac_f32_e32 v21, v22, v19
	v_fma_f32 v18, -v18, v21, v20
; __device__ __forceinline__ float bf2f(bf16_t b) { return __uint_as_float(((unsigned)b) << 16); }
; __device__ __forceinline__ float bflo(unsigned w) { return __uint_as_float(w << 16); }
; __device__ __forceinline__ float bfhi(unsigned w) { return __uint_as_float(w & 0xffff0000u); }
; __device__ __forceinline__ float gelu_tanh(float y) { const float z = 0.7978845608028654f * (y + 0.044715f * y * y * y); const float t = 1.0f - 2.0f / (__expf(2.0f * z) + 1.0f); return 0.5f * y * (1.0f + t); }
; __global__ void __launch_bounds__(512, 2) mega(Params p, int ph_lo, int ph_hi) {
;     ...
;                 for (int u = 0; u < 16; ++u) {
;                     hst = __expf(bflo(w[u])) * hst + bfhi(w[u]);
;                     XN[(trow + t0 + u) * DM + ch] = (bf16_t)(pk2(hst * gelu_tanh(bf2f(yv[u])), 0.f) & 0xffffu);
;                 }
;             }
	v_div_fmas_f32 v18, v18, v19, v21
	v_div_fixup_f32 v11, v18, v11, 2.0
	v_sub_f32_e32 v11, 1.0, v11
	v_add_f32_e32 v11, 1.0, v11
	v_mul_f32_e32 v10, v10, v11
	v_mul_f32_e32 v10, v14, v10
	v_cvt_pk_bf16_f32 v18, v10, s0
	v_add_co_u32_e32 v10, vcc, s35, v8
	s_nop 1
	v_addc_co_u32_e32 v11, vcc, 0, v9, vcc
	global_store_short v[10:11], v18, off offset:-4096
	v_lshlrev_b32_e32 v18, 16, v17
	v_mul_f32_e32 v18, 0x3fb8aa3b, v18
	v_exp_f32_e32 v18, v18
	v_and_b32_e32 v17, 0xffff0000, v17
	v_fmac_f32_e32 v17, v14, v18
	v_lshlrev_b32_e32 v14, 16, v45
	v_mul_f32_e32 v18, 0x3d372713, v14
	v_mul_f32_e32 v18, v18, v14
	v_fma_f32 v18, v18, v14, v14
	v_mul_f32_e32 v18, 0x3f4c422a, v18
	v_add_f32_e32 v18, v18, v18
	v_mul_f32_e32 v18, 0x3fb8aa3b, v18
	v_exp_f32_e32 v18, v18
	v_mul_f32_e32 v14, 0.5, v14
	v_add_f32_e32 v18, 1.0, v18
	v_div_scale_f32 v19, s[12:13], v18, v18, 2.0
	v_rcp_f32_e32 v20, v19
	s_nop 0
	v_fma_f32 v21, -v19, v20, 1.0
	v_fmac_f32_e32 v20, v21, v20
	v_div_scale_f32 v21, vcc, 2.0, v18, 2.0
	v_mul_f32_e32 v22, v21, v20
	v_fma_f32 v23, -v19, v22, v21
	v_fmac_f32_e32 v22, v23, v20
	v_fma_f32 v19, -v19, v22, v21
	v_div_fmas_f32 v19, v19, v20, v22
	v_div_fixup_f32 v18, v19, v18, 2.0
	v_sub_f32_e32 v18, 1.0, v18
	v_add_f32_e32 v18, 1.0, v18
	v_mul_f32_e32 v14, v14, v18
	v_mul_f32_e32 v14, v17, v14
	v_cvt_pk_bf16_f32 v14, v14, s0
	global_store_short v[10:11], v14, off
	v_lshlrev_b32_e32 v10, 16, v16
	v_mul_f32_e32 v10, 0x3fb8aa3b, v10
	v_exp_f32_e32 v10, v10
	v_and_b32_e32 v16, 0xffff0000, v16
	v_fmac_f32_e32 v16, v17, v10
	v_lshlrev_b32_e32 v10, 16, v28
	v_mul_f32_e32 v11, 0x3d372713, v10
	v_mul_f32_e32 v11, v11, v10
	v_fma_f32 v11, v11, v10, v10
	v_mul_f32_e32 v11, 0x3f4c422a, v11
	v_add_f32_e32 v11, v11, v11
	v_mul_f32_e32 v11, 0x3fb8aa3b, v11
	v_exp_f32_e32 v11, v11
	v_mul_f32_e32 v10, 0.5, v10
	v_add_f32_e32 v11, 1.0, v11
	v_div_scale_f32 v14, s[12:13], v11, v11, 2.0
	v_rcp_f32_e32 v17, v14
	s_nop 0
	v_fma_f32 v18, -v14, v17, 1.0
	v_fmac_f32_e32 v17, v18, v17
	v_div_scale_f32 v18, vcc, 2.0, v11, 2.0
	v_mul_f32_e32 v19, v18, v17
	v_fma_f32 v20, -v14, v19, v18
	v_fmac_f32_e32 v19, v20, v17
	v_fma_f32 v14, -v14, v19, v18
	v_div_fmas_f32 v14, v14, v17, v19
	v_div_fixup_f32 v11, v14, v11, 2.0
	v_sub_f32_e32 v11, 1.0, v11
	v_add_f32_e32 v11, 1.0, v11
	v_mul_f32_e32 v10, v10, v11
	v_mul_f32_e32 v10, v16, v10
	v_cvt_pk_bf16_f32 v14, v10, s0
	v_add_co_u32_e32 v10, vcc, s39, v8
	s_nop 1
	v_addc_co_u32_e32 v11, vcc, 0, v9, vcc
	global_store_short v[10:11], v14, off
	v_lshlrev_b32_e32 v10, 16, v15
	v_mul_f32_e32 v10, 0x3fb8aa3b, v10
	v_exp_f32_e32 v10, v10
	v_and_b32_e32 v14, 0xffff0000, v15
	v_fmac_f32_e32 v14, v16, v10
	v_lshlrev_b32_e32 v10, 16, v29
	v_mul_f32_e32 v11, 0x3d372713, v10
	v_mul_f32_e32 v11, v11, v10
	v_fma_f32 v11, v11, v10, v10
	v_mul_f32_e32 v11, 0x3f4c422a, v11
	v_add_f32_e32 v11, v11, v11
	v_mul_f32_e32 v11, 0x3fb8aa3b, v11
	v_exp_f32_e32 v11, v11
	v_mul_f32_e32 v10, 0.5, v10
	v_add_f32_e32 v11, 1.0, v11
	v_div_scale_f32 v15, s[12:13], v11, v11, 2.0
	v_rcp_f32_e32 v16, v15
	s_nop 0
	v_fma_f32 v17, -v15, v16, 1.0
	v_fmac_f32_e32 v16, v17, v16
	v_div_scale_f32 v17, vcc, 2.0, v11, 2.0
	v_mul_f32_e32 v18, v17, v16
	v_fma_f32 v19, -v15, v18, v17
	v_fmac_f32_e32 v18, v19, v16
	v_fma_f32 v15, -v15, v18, v17
	v_div_fmas_f32 v15, v15, v16, v18
	v_div_fixup_f32 v11, v15, v11, 2.0
	v_sub_f32_e32 v11, 1.0, v11
	v_add_f32_e32 v11, 1.0, v11
	v_mul_f32_e32 v10, v10, v11
	v_mul_f32_e32 v10, v14, v10
	v_add_co_u32_e32 v8, vcc, 0x680f000, v8
	v_cvt_pk_bf16_f32 v10, v10, s0
	s_nop 0
	v_addc_co_u32_e32 v9, vcc, 0, v9, vcc
	global_store_short v[8:9], v10, off
	s_cbranch_scc0 .LBB0_558
	v_add_u32_e32 v13, s38, v13
	v_cmp_lt_i32_e32 vcc, s40, v13
	s_or_b64 s[4:5], vcc, s[4:5]
	v_subrev_u16_e32 v12, s38, v12
	s_andn2_b64 exec, exec, s[4:5]
	s_cbranch_execnz .LBB0_553
